# non-temporal (nt) hint on the 8 write-once f32 output stores of the final norm loop, on top of v61
# baseline (speedup 1.0000x reference)
; template <bool HB, bool FINAL>
; __device__ __forceinline__ void norm_rows(const void* src, const bf16* y, float ys, bf16* hdst, const float* gain, bf16* xn, float* fout, float* fstage, int gw, int NGW, int lane) {
;     ...
;         for (int r = 0; r < 2; ++r) { s[r] = 0.f;
;             if (y) {
; #pragma unroll
;                 for (int j = 0; j < 4; ++j) { const u32x2 w = yw[r][j];
;                     v[r][j].x += ys * __uint_as_float(w.x << 16); v[r][j].y += ys * __uint_as_float(w.x & 0xffff0000u); v[r][j].z += ys * __uint_as_float(w.y << 16); v[r][j].w += ys * __uint_as_float(w.y & 0xffff0000u); } }
; #pragma unroll
;             for (int j = 0; j < 4; ++j) s[r] += (v[r][j].x * v[r][j].x + v[r][j].y * v[r][j].y) + (v[r][j].z * v[r][j].z + v[r][j].w * v[r][j].w); }
; #pragma unroll
;         for (int o = 1; o < 64; o <<= 1) { s[0] += __shfl_xor(s[0], o); s[1] += __shfl_xor(s[1], o); }
.LF_C:
	s_lshl_b64 s[6:7], s[6:7], 12
	v_lshlrev_b32_e32 v24, 16, v26
	v_and_b32_e32 v25, 0xffff0000, v26
	v_lshlrev_b32_e32 v64, 16, v28
	v_and_b32_e32 v65, 0xffff0000, v28
	v_lshlrev_b32_e32 v26, 16, v27
	v_and_b32_e32 v27, 0xffff0000, v27
	v_lshlrev_b32_e32 v28, 16, v29
	v_and_b32_e32 v29, 0xffff0000, v29
	v_pk_fma_f32 v[24:25], v[64:65], 0.5, v[24:25] op_sel_hi:[1,0,1]
	v_pk_fma_f32 v[26:27], v[28:29], 0.5, v[26:27] op_sel_hi:[1,0,1]
	v_lshlrev_b32_e32 v28, 16, v30
	v_and_b32_e32 v29, 0xffff0000, v30
	v_lshlrev_b32_e32 v64, 16, v32
	v_and_b32_e32 v65, 0xffff0000, v32
	v_lshlrev_b32_e32 v30, 16, v31
	v_and_b32_e32 v31, 0xffff0000, v31
	v_lshlrev_b32_e32 v32, 16, v33
	v_and_b32_e32 v33, 0xffff0000, v33
	v_pk_fma_f32 v[28:29], v[64:65], 0.5, v[28:29] op_sel_hi:[1,0,1]
	v_pk_fma_f32 v[30:31], v[32:33], 0.5, v[30:31] op_sel_hi:[1,0,1]
	v_lshlrev_b32_e32 v32, 16, v34
	v_and_b32_e32 v33, 0xffff0000, v34
	v_lshlrev_b32_e32 v64, 16, v36
	v_and_b32_e32 v65, 0xffff0000, v36
	v_lshlrev_b32_e32 v34, 16, v35
	v_and_b32_e32 v35, 0xffff0000, v35
	v_lshlrev_b32_e32 v36, 16, v37
	v_and_b32_e32 v37, 0xffff0000, v37
	v_pk_fma_f32 v[32:33], v[64:65], 0.5, v[32:33] op_sel_hi:[1,0,1]
	v_pk_fma_f32 v[34:35], v[36:37], 0.5, v[34:35] op_sel_hi:[1,0,1]
	v_lshlrev_b32_e32 v36, 16, v40
	v_and_b32_e32 v37, 0xffff0000, v40
	v_lshlrev_b32_e32 v64, 16, v62
	v_and_b32_e32 v65, 0xffff0000, v62
	v_pk_fma_f32 v[36:37], v[64:65], 0.5, v[36:37] op_sel_hi:[1,0,1]
	v_lshlrev_b32_e32 v40, 16, v41
	v_and_b32_e32 v41, 0xffff0000, v41
	v_lshlrev_b32_e32 v62, 16, v63
	v_and_b32_e32 v63, 0xffff0000, v63
	v_mov_b32_e32 v64, v25
	v_mov_b32_e32 v65, v27
	v_pk_fma_f32 v[40:41], v[62:63], 0.5, v[40:41] op_sel_hi:[1,0,1]
	v_mov_b32_e32 v62, v24
	v_mov_b32_e32 v63, v26
	v_pk_mul_f32 v[64:65], v[64:65], v[64:65]
	v_mov_b32_e32 v66, v29
	v_mov_b32_e32 v67, v31
	v_pk_fma_f32 v[62:63], v[62:63], v[62:63], v[64:65]
	v_mov_b32_e32 v64, v28
	v_mov_b32_e32 v65, v30
	v_pk_mul_f32 v[66:67], v[66:67], v[66:67]
	v_mul_f32_e32 v0, v33, v33
	v_pk_fma_f32 v[64:65], v[64:65], v[64:65], v[66:67]
	v_pk_fma_f32 v[66:67], v[32:33], v[32:33], v[0:1] op_sel_hi:[1,1,0]
	v_mul_f32_e32 v0, v35, v35
	v_pk_add_f32 v[62:63], v[62:63], v[62:63] op_sel:[0,1] op_sel_hi:[1,0]
	v_pk_add_f32 v[64:65], v[64:65], v[64:65] op_sel:[0,1] op_sel_hi:[1,0]
	v_pk_fma_f32 v[68:69], v[34:35], v[34:35], v[0:1] op_sel_hi:[1,1,0]
	v_pk_mul_f32 v[70:71], v[36:37], v[36:37]
	v_pk_mul_f32 v[72:73], v[40:41], v[40:41]
	v_mov_b32_e32 v63, v70
	v_mov_b32_e32 v65, v71
	v_mov_b32_e32 v67, v72
	v_mov_b32_e32 v69, v73
	v_pk_add_f32 v[62:63], v[62:63], v[64:65]
	v_pk_add_f32 v[64:65], v[66:67], v[68:69]
	v_lshlrev_b32_e32 v66, 16, v54
	v_pk_add_f32 v[62:63], v[62:63], v[64:65]
	v_lshlrev_b32_e32 v64, 16, v50
	v_and_b32_e32 v65, 0xffff0000, v50
	v_and_b32_e32 v67, 0xffff0000, v54
	v_lshlrev_b32_e32 v50, 16, v51
	v_and_b32_e32 v51, 0xffff0000, v51
	v_lshlrev_b32_e32 v54, 16, v55
	v_and_b32_e32 v55, 0xffff0000, v55
	v_pk_fma_f32 v[64:65], v[66:67], 0.5, v[64:65] op_sel_hi:[1,0,1]
	v_pk_fma_f32 v[50:51], v[54:55], 0.5, v[50:51] op_sel_hi:[1,0,1]
	v_lshlrev_b32_e32 v54, 16, v46
	v_and_b32_e32 v55, 0xffff0000, v46
	v_lshlrev_b32_e32 v66, 16, v52
	v_and_b32_e32 v67, 0xffff0000, v52
	v_lshlrev_b32_e32 v46, 16, v47
	v_and_b32_e32 v47, 0xffff0000, v47
	v_lshlrev_b32_e32 v52, 16, v53
	v_and_b32_e32 v53, 0xffff0000, v53
	v_pk_fma_f32 v[54:55], v[66:67], 0.5, v[54:55] op_sel_hi:[1,0,1]
	v_pk_fma_f32 v[46:47], v[52:53], 0.5, v[46:47] op_sel_hi:[1,0,1]
	v_lshlrev_b32_e32 v52, 16, v42
	v_and_b32_e32 v53, 0xffff0000, v42
	v_lshlrev_b32_e32 v66, 16, v48
	v_and_b32_e32 v67, 0xffff0000, v48
	v_lshlrev_b32_e32 v42, 16, v43
	v_and_b32_e32 v43, 0xffff0000, v43
	v_lshlrev_b32_e32 v48, 16, v49
	v_and_b32_e32 v49, 0xffff0000, v49
	v_pk_fma_f32 v[52:53], v[66:67], 0.5, v[52:53] op_sel_hi:[1,0,1]
	v_pk_fma_f32 v[42:43], v[48:49], 0.5, v[42:43] op_sel_hi:[1,0,1]
	v_lshlrev_b32_e32 v48, 16, v38
	v_and_b32_e32 v49, 0xffff0000, v38
	v_lshlrev_b32_e32 v66, 16, v44
	v_and_b32_e32 v67, 0xffff0000, v44
	v_pk_fma_f32 v[48:49], v[66:67], 0.5, v[48:49] op_sel_hi:[1,0,1]
	v_lshlrev_b32_e32 v38, 16, v39
	v_and_b32_e32 v39, 0xffff0000, v39
	v_lshlrev_b32_e32 v44, 16, v45
	v_and_b32_e32 v45, 0xffff0000, v45
	v_mov_b32_e32 v66, v65
	v_mov_b32_e32 v67, v51
	v_pk_fma_f32 v[38:39], v[44:45], 0.5, v[38:39] op_sel_hi:[1,0,1]
	v_mov_b32_e32 v44, v64
	v_mov_b32_e32 v45, v50
	v_pk_mul_f32 v[66:67], v[66:67], v[66:67]
	v_mov_b32_e32 v68, v55
	v_mov_b32_e32 v69, v47
	v_pk_fma_f32 v[44:45], v[44:45], v[44:45], v[66:67]
	v_mov_b32_e32 v66, v54
	v_mov_b32_e32 v67, v46
	v_pk_mul_f32 v[68:69], v[68:69], v[68:69]
	v_mul_f32_e32 v0, v53, v53
	v_pk_fma_f32 v[66:67], v[66:67], v[66:67], v[68:69]
	v_pk_fma_f32 v[68:69], v[52:53], v[52:53], v[0:1] op_sel_hi:[1,1,0]
	v_mul_f32_e32 v0, v43, v43
	v_pk_add_f32 v[44:45], v[44:45], v[44:45] op_sel:[0,1] op_sel_hi:[1,0]
	v_pk_add_f32 v[66:67], v[66:67], v[66:67] op_sel:[0,1] op_sel_hi:[1,0]
	v_pk_fma_f32 v[70:71], v[42:43], v[42:43], v[0:1] op_sel_hi:[1,1,0]
	v_pk_mul_f32 v[72:73], v[48:49], v[48:49]
	v_pk_mul_f32 v[74:75], v[38:39], v[38:39]
	v_mov_b32_e32 v45, v72
	v_mov_b32_e32 v67, v73
	v_mov_b32_e32 v69, v74
	v_mov_b32_e32 v71, v75
	v_pk_add_f32 v[44:45], v[44:45], v[66:67]
	v_pk_add_f32 v[66:67], v[68:69], v[70:71]
	v_mov_b32_e32 v69, v62
	v_pk_add_f32 v[44:45], v[44:45], v[66:67]
	v_lshl_add_u64 v[66:67], v[22:23], 0, s[6:7]
	v_mov_b32_e32 v68, v44
	v_mov_b32_e32 v62, v45
	v_pk_add_f32 v[44:45], v[68:69], v[62:63]
	ds_bpermute_b32 v63, v56, v45
	ds_bpermute_b32 v62, v56, v44
	s_mov_b32 s6, 0x3a800000
	s_waitcnt lgkmcnt(0)
; __device__ __forceinline__ unsigned cvt_pk_bf16(float lo, float hi) { f32x2_t v = {lo, hi}; bf16x2_t b = __builtin_convertvector(v, bf16x2_t); return __builtin_bit_cast(unsigned, b); }
; template <bool HB, bool FINAL>
; __device__ __forceinline__ void norm_rows(const void* src, const bf16* y, float ys, bf16* hdst, const float* gain, bf16* xn, float* fout, float* fstage, int gw, int NGW, int lane) {
;     ...
;         for (int o = 1; o < 64; o <<= 1) { s[0] += __shfl_xor(s[0], o); s[1] += __shfl_xor(s[1], o); }
; #pragma unroll
;         for (int r = 0; r < 2; ++r) { const int m = m0 + r * NGW; const float rstd = rsqrtf(s[r] * (1.f / D) + EPS);
;             if (!FINAL && hdst) { u32x2* hr = (u32x2*)(hdst + (size_t)m * D) + lane;
; #pragma unroll
;                 for (int j = 0; j < 4; ++j) { u32x2 w; w.x = cvt_pk_bf16(v[r][j].x, v[r][j].y); w.y = cvt_pk_bf16(v[r][j].z, v[r][j].w); hr[64 * j] = w; } }
;             if (FINAL) { f32x4* o = (f32x4*)((m >= T / 2 ? fout : fstage) + (size_t)m * D) + lane;
; #pragma unroll
;                 for (int j = 0; j < 4; ++j) o[64 * j] = v[r][j] * rstd * gv[j];
	v_pk_add_f32 v[44:45], v[44:45], v[62:63]
	ds_bpermute_b32 v63, v57, v45
	ds_bpermute_b32 v62, v57, v44
	s_waitcnt lgkmcnt(0)
	v_pk_add_f32 v[44:45], v[44:45], v[62:63]
	ds_bpermute_b32 v63, v58, v45
	ds_bpermute_b32 v62, v58, v44
	s_waitcnt lgkmcnt(0)
	v_pk_add_f32 v[44:45], v[44:45], v[62:63]
	ds_bpermute_b32 v63, v59, v45
	ds_bpermute_b32 v62, v59, v44
	s_waitcnt lgkmcnt(0)
	v_pk_add_f32 v[44:45], v[44:45], v[62:63]
	ds_bpermute_b32 v63, v60, v45
	ds_bpermute_b32 v62, v60, v44
	s_waitcnt lgkmcnt(0)
	v_pk_add_f32 v[44:45], v[44:45], v[62:63]
	ds_bpermute_b32 v63, v61, v45
	ds_bpermute_b32 v62, v61, v44
	s_waitcnt lgkmcnt(0)
	v_pk_add_f32 v[44:45], v[44:45], v[62:63]
	s_nop 0
	v_pk_fma_f32 v[44:45], v[44:45], s[6:7], v[142:143] op_sel_hi:[1,0,0]
	s_nop 0
	v_mul_f32_e32 v0, 0x4b800000, v45
	v_cmp_gt_f32_e64 s[6:7], s72, v45
	v_cmp_gt_f32_e32 vcc, s72, v44
	s_nop 0
	v_cndmask_b32_e64 v0, v45, v0, s[6:7]
	v_rsq_f32_e32 v0, v0
	s_nop 0
	v_mul_f32_e32 v45, 0x45800000, v0
	v_cndmask_b32_e64 v0, v0, v45, s[6:7]
	v_pk_mul_f32 v[24:25], v[24:25], v[0:1] op_sel_hi:[1,0]
	v_pk_mul_f32 v[26:27], v[26:27], v[0:1] op_sel_hi:[1,0]
	v_pk_mul_f32 v[24:25], v[2:3], v[24:25]
	v_pk_mul_f32 v[26:27], v[4:5], v[26:27]
	global_store_dwordx4 v[66:67], v[24:27], off nt
	s_lshl_b64 s[6:7], s[8:9], 12
	s_nop 0
	v_pk_mul_f32 v[24:25], v[28:29], v[0:1] op_sel_hi:[1,0]
	v_pk_mul_f32 v[26:27], v[30:31], v[0:1] op_sel_hi:[1,0]
	v_pk_mul_f32 v[24:25], v[6:7], v[24:25]
	v_pk_mul_f32 v[26:27], v[8:9], v[26:27]
	global_store_dwordx4 v[66:67], v[24:27], off offset:1024 nt
	v_lshl_add_u64 v[28:29], v[22:23], 0, s[6:7]
	s_add_i32 s6, s8, s33
	v_pk_mul_f32 v[24:25], v[32:33], v[0:1] op_sel_hi:[1,0]
	v_pk_mul_f32 v[26:27], v[34:35], v[0:1] op_sel_hi:[1,0]
	v_pk_mul_f32 v[24:25], v[10:11], v[24:25]
	v_pk_mul_f32 v[26:27], v[12:13], v[26:27]
	global_store_dwordx4 v[66:67], v[24:27], off offset:2048 nt
	s_cmpk_gt_i32 s6, 0x7fff
	s_nop 0
	v_pk_mul_f32 v[24:25], v[36:37], v[0:1] op_sel_hi:[1,0]
	v_pk_mul_f32 v[26:27], v[40:41], v[0:1] op_sel_hi:[1,0]
	v_mul_f32_e32 v0, 0x4b800000, v44
	v_cndmask_b32_e32 v0, v44, v0, vcc
	v_rsq_f32_e32 v0, v0
	v_pk_mul_f32 v[26:27], v[16:17], v[26:27]
	v_pk_mul_f32 v[24:25], v[14:15], v[24:25]
	global_store_dwordx4 v[66:67], v[24:27], off offset:3072 nt
	s_nop 1
	v_mul_f32_e32 v24, 0x45800000, v0
	v_cndmask_b32_e32 v0, v0, v24, vcc
	v_pk_mul_f32 v[24:25], v[64:65], v[0:1] op_sel_hi:[1,0]
	v_pk_mul_f32 v[26:27], v[50:51], v[0:1] op_sel_hi:[1,0]
	v_pk_mul_f32 v[24:25], v[2:3], v[24:25]
	v_pk_mul_f32 v[26:27], v[4:5], v[26:27]
	global_store_dwordx4 v[28:29], v[24:27], off nt
	s_nop 1
	v_pk_mul_f32 v[24:25], v[54:55], v[0:1] op_sel_hi:[1,0]
	v_pk_mul_f32 v[26:27], v[46:47], v[0:1] op_sel_hi:[1,0]
	v_pk_mul_f32 v[24:25], v[6:7], v[24:25]
	v_pk_mul_f32 v[26:27], v[8:9], v[26:27]
	global_store_dwordx4 v[28:29], v[24:27], off offset:1024 nt
	s_nop 1
	v_pk_mul_f32 v[24:25], v[52:53], v[0:1] op_sel_hi:[1,0]
	v_pk_mul_f32 v[26:27], v[42:43], v[0:1] op_sel_hi:[1,0]
	v_pk_mul_f32 v[24:25], v[10:11], v[24:25]
	v_pk_mul_f32 v[26:27], v[12:13], v[26:27]
	global_store_dwordx4 v[28:29], v[24:27], off offset:2048 nt
	s_nop 1
	v_pk_mul_f32 v[24:25], v[48:49], v[0:1] op_sel_hi:[1,0]
	v_pk_mul_f32 v[26:27], v[38:39], v[0:1] op_sel_hi:[1,0]
	v_pk_mul_f32 v[24:25], v[14:15], v[24:25]
	v_pk_mul_f32 v[26:27], v[16:17], v[26:27]
	global_store_dwordx4 v[28:29], v[24:27], off offset:3072 nt
	s_cbranch_scc1 .LF_exit
	s_waitcnt vmcnt(8)
	s_branch .LF_copy
